# v27: v26 + LDS loads of the peeled last attention K/V tile issued one load ahead (waits recomputed)
# baseline (speedup 1.0000x reference)
.Lpop_skip:
	s_mov_b64 exec, s[100:101]
	v_mov_b32_e32 v235, 1
	s_load_dwordx2 s[100:101], s[44:45], 0x80
	ds_read_b128 v[200:203], v137 offset:39232
	s_waitcnt lgkmcnt(1)
	v_readlane_b32 s14, v255, 36
	v_mfma_f32_16x16x32_bf16 v[82:85], v[82:85], v[14:17], 0
	ds_read_b128 v[204:207], v137 offset:47936
	v_readlane_b32 s15, v255, 37
	s_lshl_b64 s[14:15], s[14:15], 2
	v_mfma_f32_16x16x32_bf16 v[86:89], v[90:93], v[2:5], v[86:89]
	ds_read_b128 v[208:211], v137 offset:39168
	v_mfma_f32_16x16x32_bf16 v[82:85], v[90:93], v[6:9], v[82:85]
	ds_read_b128 v[212:215], v137 offset:43520
	s_nop 4
	v_exp_f32_e32 v116, v86
	v_exp_f32_e32 v114, v87
	s_waitcnt lgkmcnt(1)
	v_mfma_f32_16x16x32_bf16 v[94:97], v[208:211], v[10:13], 0
	v_exp_f32_e32 v134, v82
	v_exp_f32_e32 v132, v83
	v_exp_f32_e32 v130, v84
	v_mfma_f32_16x16x32_bf16 v[90:93], v[208:211], v[14:17], 0
	v_exp_f32_e32 v128, v85
	ds_read_b128 v[208:211], v137 offset:43584
	v_exp_f32_e32 v112, v88
	v_mfma_f32_16x16x32_bf16 v[90:93], v[200:203], v[6:9], v[90:93]
	v_exp_f32_e32 v110, v89
	v_mfma_f32_16x16x32_bf16 v[94:97], v[200:203], v[2:5], v[94:97]
	s_nop 1
	v_cvt_pk_bf16_f32 v98, v134, v132
	s_nop 1
	s_nop 5
	v_exp_f32_e32 v126, v90
	v_exp_f32_e32 v124, v91
	v_exp_f32_e32 v120, v92
	v_exp_f32_e32 v118, v93
	ds_read_b128 v[200:203], v137 offset:47872
	s_waitcnt lgkmcnt(2)
	v_mfma_f32_16x16x32_bf16 v[86:89], v[212:215], v[10:13], 0
	v_exp_f32_e32 v108, v94
	v_exp_f32_e32 v106, v95
	v_exp_f32_e32 v104, v96
	v_mfma_f32_16x16x32_bf16 v[82:85], v[212:215], v[14:17], 0
	v_exp_f32_e32 v102, v97
	s_nop 1
	v_cvt_pk_bf16_f32 v94, v116, v114
	s_nop 1
	s_nop 1
	v_cvt_pk_bf16_f32 v95, v112, v110
	s_nop 1
	s_waitcnt lgkmcnt(1)
	v_mfma_f32_16x16x32_bf16 v[82:85], v[208:211], v[6:9], v[82:85]
	s_nop 1
	v_cvt_pk_bf16_f32 v96, v108, v106
	s_nop 1
	s_nop 1
	v_cvt_pk_bf16_f32 v97, v104, v102
	s_nop 1
	s_nop 1
	v_cvt_pk_bf16_f32 v99, v130, v128
	s_nop 1
	v_mfma_f32_16x16x32_bf16 v[86:89], v[208:211], v[2:5], v[86:89]
	ds_read_b128 v[208:211], v183 offset:34816
	s_nop 5
	v_exp_f32_e32 v135, v82
	v_exp_f32_e32 v133, v83
	v_exp_f32_e32 v131, v84
	v_exp_f32_e32 v129, v85
	ds_read_b128 v[212:215], v183 offset:34880
	s_nop 1
	v_cvt_pk_bf16_f32 v100, v126, v124
	s_nop 1
	s_nop 1
	v_cvt_pk_bf16_f32 v101, v120, v118
	s_nop 1
	s_waitcnt lgkmcnt(1)
	v_mfma_f32_16x16x32_bf16 v[78:81], v[208:211], v[94:97], v[78:81]
	v_exp_f32_e32 v117, v86
	v_exp_f32_e32 v115, v87
	v_exp_f32_e32 v113, v88
	v_mfma_f32_16x16x32_bf16 v[74:77], v[208:211], v[98:101], v[74:77]
	ds_read_b128 v[208:211], v183 offset:39168
	v_exp_f32_e32 v111, v89
	v_mfma_f32_16x16x32_bf16 v[138:141], v[200:203], v[10:13], 0
	v_mfma_f32_16x16x32_bf16 v[90:93], v[200:203], v[14:17], 0
	v_mfma_f32_16x16x32_bf16 v[90:93], v[204:207], v[6:9], v[90:93]
	v_mfma_f32_16x16x32_bf16 v[138:141], v[204:207], v[2:5], v[138:141]
	s_nop 1
	v_cvt_pk_bf16_f32 v142, v135, v133
	s_nop 1
	s_nop 6
	v_exp_f32_e32 v127, v90
	v_exp_f32_e32 v125, v91
	v_exp_f32_e32 v121, v92
	v_exp_f32_e32 v119, v93
	s_nop 1
	v_cvt_pk_bf16_f32 v143, v131, v129
	s_nop 1
	s_nop 1
	v_cvt_pk_bf16_f32 v144, v127, v125
	s_nop 1
	s_nop 1
	v_cvt_pk_bf16_f32 v145, v121, v119
	s_nop 1
	v_exp_f32_e32 v109, v138
	s_waitcnt lgkmcnt(1)
	v_mfma_f32_16x16x32_bf16 v[90:93], v[212:215], v[142:145], v[74:77]
	v_exp_f32_e32 v107, v139
	v_exp_f32_e32 v105, v140
	v_exp_f32_e32 v103, v141
	ds_read_b128 v[200:203], v183 offset:39232
	s_waitcnt lgkmcnt(1)
	v_mfma_f32_16x16x32_bf16 v[70:73], v[208:211], v[94:97], v[70:73]
	s_nop 1
	v_cvt_pk_bf16_f32 v138, v117, v115
	s_nop 1
	s_nop 1
	v_cvt_pk_bf16_f32 v139, v113, v111
	s_nop 1
	s_nop 1
	v_cvt_pk_bf16_f32 v140, v109, v107
	s_nop 1
	v_mfma_f32_16x16x32_bf16 v[62:65], v[208:211], v[98:101], v[62:65]
	ds_read_b128 v[204:207], v183 offset:43520
	s_nop 1
	v_cvt_pk_bf16_f32 v141, v105, v103
	s_nop 1
	s_waitcnt lgkmcnt(1)
	v_mfma_f32_16x16x32_bf16 v[86:89], v[200:203], v[142:145], v[62:65]
	s_nop 4
	ds_read_b128 v[208:211], v183 offset:43584
	s_waitcnt lgkmcnt(1)
	v_mfma_f32_16x16x32_bf16 v[66:69], v[204:207], v[94:97], v[66:69]
	v_mfma_f32_16x16x32_bf16 v[46:49], v[204:207], v[98:101], v[46:49]
	ds_read_b128 v[204:207], v183 offset:47872
	v_mfma_f32_16x16x32_bf16 v[78:81], v[212:215], v[138:141], v[78:81]
	v_mfma_f32_16x16x32_bf16 v[82:85], v[200:203], v[138:141], v[70:73]
	s_waitcnt lgkmcnt(1)
	v_mfma_f32_16x16x32_bf16 v[74:77], v[208:211], v[142:145], v[46:49]
	s_nop 2
	ds_read_b128 v[200:203], v183 offset:47936
	s_waitcnt lgkmcnt(1)
	v_mfma_f32_16x16x32_bf16 v[58:61], v[204:207], v[94:97], v[58:61]
	v_mfma_f32_16x16x32_bf16 v[38:41], v[204:207], v[98:101], v[38:41]
	ds_read_b128 v[204:207], v183 offset:52224
	v_mfma_f32_16x16x32_bf16 v[70:73], v[208:211], v[138:141], v[66:69]
	s_waitcnt lgkmcnt(1)
	v_mfma_f32_16x16x32_bf16 v[66:69], v[200:203], v[142:145], v[38:41]
	s_nop 3
	ds_read_b128 v[208:211], v183 offset:52288
	v_mfma_f32_16x16x32_bf16 v[62:65], v[200:203], v[138:141], v[58:61]
	s_waitcnt lgkmcnt(1)
	v_mfma_f32_16x16x32_bf16 v[46:49], v[204:207], v[94:97], v[54:57]
	v_mfma_f32_16x16x32_bf16 v[30:33], v[204:207], v[98:101], v[30:33]
	ds_read_b128 v[200:203], v183 offset:56576
	s_waitcnt lgkmcnt(1)
	v_mfma_f32_16x16x32_bf16 v[58:61], v[208:211], v[142:145], v[30:33]
	s_nop 4
	ds_read_b128 v[204:207], v137 offset:52288
	v_mfma_f32_16x16x32_bf16 v[54:57], v[208:211], v[138:141], v[46:49]
	s_waitcnt lgkmcnt(1)
	v_mfma_f32_16x16x32_bf16 v[38:41], v[200:203], v[94:97], v[50:53]
	s_nop 2
	ds_read_b128 v[208:211], v183 offset:56640
	v_mfma_f32_16x16x32_bf16 v[26:29], v[200:203], v[98:101], v[26:29]
	ds_read_b128 v[200:203], v183 offset:60928
	s_waitcnt lgkmcnt(1)
	v_mfma_f32_16x16x32_bf16 v[46:49], v[208:211], v[142:145], v[26:29]
	s_nop 4
	ds_read_b128 v[212:215], v183 offset:60992
	v_mfma_f32_16x16x32_bf16 v[38:41], v[208:211], v[138:141], v[38:41]
	s_waitcnt lgkmcnt(1)
	v_mfma_f32_16x16x32_bf16 v[30:33], v[200:203], v[94:97], v[42:45]
	s_nop 2
	ds_read_b128 v[208:211], v183 offset:65344
	v_mfma_f32_16x16x32_bf16 v[22:25], v[200:203], v[98:101], v[22:25]
	s_waitcnt lgkmcnt(1)
	v_mfma_f32_16x16x32_bf16 v[26:29], v[212:215], v[138:141], v[30:33]
	v_mfma_f32_16x16x32_bf16 v[30:33], v[212:215], v[142:145], v[22:25]
	ds_read_b128 v[200:203], v183 offset:65280
	s_nop 3
	ds_read_b128 v[212:215], v137 offset:56640
	s_waitcnt lgkmcnt(1)
	v_mfma_f32_16x16x32_bf16 v[34:37], v[200:203], v[94:97], v[34:37]
	v_mfma_f32_16x16x32_bf16 v[22:25], v[200:203], v[98:101], v[18:21]
	ds_read_b128 v[200:203], v137 offset:52224
	v_mfma_f32_16x16x32_bf16 v[18:21], v[208:211], v[138:141], v[34:37]
	s_nop 4
	ds_read_b128 v[216:219], v137 offset:56576
	v_mfma_f32_16x16x32_bf16 v[22:25], v[208:211], v[142:145], v[22:25]
	s_waitcnt lgkmcnt(1)
	v_mfma_f32_16x16x32_bf16 v[42:45], v[200:203], v[10:13], 0
	v_mfma_f32_16x16x32_bf16 v[34:37], v[200:203], v[14:17], 0
	v_mfma_f32_16x16x32_bf16 v[42:45], v[204:207], v[2:5], v[42:45]
	v_mfma_f32_16x16x32_bf16 v[34:37], v[204:207], v[6:9], v[34:37]
	ds_read_b128 v[200:203], v137 offset:60928
	s_nop 5
	v_exp_f32_e32 v158, v42
	v_exp_f32_e32 v156, v43
	s_waitcnt lgkmcnt(1)
	v_mfma_f32_16x16x32_bf16 v[94:97], v[216:219], v[10:13], 0
	v_exp_f32_e32 v172, v34
	v_exp_f32_e32 v174, v35
	v_pk_add_f32 v[34:35], v[134:135], 0 op_sel_hi:[1,0]
	v_mfma_f32_16x16x32_bf16 v[50:53], v[216:219], v[14:17], 0
	v_add_f32_e64 v34, v132, v34
	v_add_f32_e64 v35, v133, v35
	v_exp_f32_e32 v170, v36
	v_pk_add_f32 v[34:35], v[130:131], v[34:35]
	v_mfma_f32_16x16x32_bf16 v[50:53], v[212:215], v[6:9], v[50:53]
	v_add_f32_e64 v34, v128, v34
	v_add_f32_e64 v35, v129, v35
	v_exp_f32_e32 v166, v37
	v_pk_add_f32 v[34:35], v[34:35], v[126:127]
	v_exp_f32_e32 v154, v44
	v_pk_add_f32 v[34:35], v[124:125], v[34:35]
	s_nop 1
	v_exp_f32_e32 v168, v50
	v_pk_add_f32 v[34:35], v[120:121], v[34:35]
	v_exp_f32_e32 v164, v51
	v_pk_add_f32 v[118:119], v[118:119], v[34:35]
	ds_read_b128 v[204:207], v137 offset:60992
	v_exp_f32_e32 v160, v52
	v_exp_f32_e32 v162, v53
	ds_read_b128 v[208:211], v137 offset:65280
	v_exp_f32_e32 v144, v45
	s_waitcnt lgkmcnt(2)
	v_mfma_f32_16x16x32_bf16 v[42:45], v[200:203], v[10:13], 0
	v_mfma_f32_16x16x32_bf16 v[34:37], v[200:203], v[14:17], 0
	s_waitcnt lgkmcnt(1)
	v_mfma_f32_16x16x32_bf16 v[42:45], v[204:207], v[2:5], v[42:45]
	v_mfma_f32_16x16x32_bf16 v[34:37], v[204:207], v[6:9], v[34:37]
	ds_read_b128 v[200:203], v137 offset:65344
	s_nop 5
	v_exp_f32_e32 v159, v42
	v_exp_f32_e32 v157, v43
	s_waitcnt lgkmcnt(1)
	v_mfma_f32_16x16x32_bf16 v[10:13], v[208:211], v[10:13], 0
	v_exp_f32_e32 v173, v34
	v_exp_f32_e32 v175, v35
	v_exp_f32_e32 v171, v36
	v_mfma_f32_16x16x32_bf16 v[14:17], v[208:211], v[14:17], 0
	ds_read_b128 v[204:207], v183 offset:35008
	v_exp_f32_e32 v167, v37
	s_nop 1
	v_cvt_pk_bf16_f32 v128, v173, v175
	s_nop 1
	v_mfma_f32_16x16x32_bf16 v[94:97], v[212:215], v[2:5], v[94:97]
	s_nop 1
	v_cvt_pk_bf16_f32 v98, v172, v174
	s_nop 1
	s_nop 1
	v_cvt_pk_bf16_f32 v99, v170, v166
	s_nop 1
	s_nop 1
	v_cvt_pk_bf16_f32 v100, v168, v164
	s_nop 1
	s_waitcnt lgkmcnt(1)
	v_mfma_f32_16x16x32_bf16 v[2:5], v[200:203], v[2:5], v[10:13]
	s_nop 1
	v_cvt_pk_bf16_f32 v101, v160, v162
	s_nop 1
	s_nop 5
	v_exp_f32_e32 v142, v94
	ds_read_b128 v[208:211], v183 offset:34944
	v_exp_f32_e32 v143, v2
	v_exp_f32_e32 v141, v3
	v_exp_f32_e32 v139, v4
	v_exp_f32_e32 v137, v5
	ds_read_b128 v[212:215], v183 offset:39296
	v_mfma_f32_16x16x32_bf16 v[6:9], v[200:203], v[6:9], v[14:17]
	v_exp_f32_e32 v140, v95
	v_exp_f32_e32 v138, v96
	v_exp_f32_e32 v136, v97
	s_nop 1
	v_cvt_pk_bf16_f32 v94, v158, v156
	s_nop 1
	s_nop 1
	v_cvt_pk_bf16_f32 v95, v154, v144
	s_nop 1
	s_nop 1
	v_cvt_pk_bf16_f32 v96, v142, v140
	s_nop 1
	s_nop 1
	v_cvt_pk_bf16_f32 v97, v138, v136
	s_nop 1
	s_nop 4
	v_exp_f32_e32 v169, v6
	v_exp_f32_e32 v165, v7
	v_exp_f32_e32 v161, v8
	v_exp_f32_e32 v163, v9
	s_waitcnt lgkmcnt(1)
	v_mfma_f32_16x16x32_bf16 v[6:9], v[208:211], v[94:97], v[78:81]
	s_nop 1
	v_cvt_pk_bf16_f32 v129, v171, v167
	s_nop 1
	s_nop 1
	v_cvt_pk_bf16_f32 v130, v169, v165
	s_nop 1
	s_nop 1
	v_cvt_pk_bf16_f32 v131, v161, v163
	s_nop 1
	v_mfma_f32_16x16x32_bf16 v[2:5], v[208:211], v[98:101], v[90:93]
	v_exp_f32_e32 v155, v44
	v_exp_f32_e32 v145, v45
	s_nop 1
	v_cvt_pk_bf16_f32 v124, v159, v157
	s_nop 1
	v_mfma_f32_16x16x32_bf16 v[90:93], v[204:207], v[128:131], v[2:5]
	s_nop 1
	v_cvt_pk_bf16_f32 v125, v155, v145
	s_nop 1
	s_nop 1
	v_cvt_pk_bf16_f32 v126, v143, v141
	s_nop 1
	s_nop 1
	v_cvt_pk_bf16_f32 v127, v139, v137
	s_nop 1
	s_nop 0
	v_mfma_f32_16x16x32_bf16 v[78:81], v[204:207], v[124:127], v[6:9]
	s_nop 2
	ds_read_b128 v[200:203], v183 offset:39360
	ds_read_b128 v[204:207], v183 offset:43648
	s_waitcnt lgkmcnt(2)
	v_mfma_f32_16x16x32_bf16 v[6:9], v[212:215], v[94:97], v[82:85]
	v_mfma_f32_16x16x32_bf16 v[2:5], v[212:215], v[98:101], v[86:89]
	s_waitcnt lgkmcnt(1)
	v_mfma_f32_16x16x32_bf16 v[50:53], v[200:203], v[128:131], v[2:5]
	v_mfma_f32_16x16x32_bf16 v[14:17], v[200:203], v[124:127], v[6:9]
	s_nop 4
	ds_read_b128 v[200:203], v183 offset:43712
	ds_read_b128 v[208:211], v183 offset:48000
	s_waitcnt lgkmcnt(2)
	v_mfma_f32_16x16x32_bf16 v[6:9], v[204:207], v[94:97], v[70:73]
	v_mfma_f32_16x16x32_bf16 v[2:5], v[204:207], v[98:101], v[74:77]
	s_waitcnt lgkmcnt(1)
	v_mfma_f32_16x16x32_bf16 v[34:37], v[200:203], v[128:131], v[2:5]
	v_mfma_f32_16x16x32_bf16 v[6:9], v[200:203], v[124:127], v[6:9]
	s_nop 4
	ds_read_b128 v[200:203], v183 offset:48064
	s_waitcnt lgkmcnt(1)
	v_mfma_f32_16x16x32_bf16 v[10:13], v[208:211], v[94:97], v[62:65]
	s_nop 2
	v_mfma_f32_16x16x32_bf16 v[42:45], v[208:211], v[98:101], v[66:69]
	s_waitcnt lgkmcnt(0)
	v_mfma_f32_16x16x32_bf16 v[2:5], v[200:203], v[124:127], v[10:13]
	v_mfma_f32_16x16x32_bf16 v[10:13], v[200:203], v[128:131], v[42:45]
	ds_read_b128 v[200:203], v183 offset:52352
	ds_read_b128 v[62:65], v183 offset:52416
	s_nop 3
	ds_read_b128 v[204:207], v183 offset:56704
	s_waitcnt lgkmcnt(2)
	v_mfma_f32_16x16x32_bf16 v[54:57], v[200:203], v[94:97], v[54:57]
	v_mfma_f32_16x16x32_bf16 v[58:61], v[200:203], v[98:101], v[58:61]
	s_waitcnt lgkmcnt(1)
	v_mfma_f32_16x16x32_bf16 v[42:45], v[62:65], v[124:127], v[54:57]
	v_mfma_f32_16x16x32_bf16 v[54:57], v[62:65], v[128:131], v[58:61]
	s_nop 5
	ds_read_b128 v[200:203], v183 offset:56768
	s_waitcnt lgkmcnt(1)
	v_mfma_f32_16x16x32_bf16 v[38:41], v[204:207], v[94:97], v[38:41]
	v_mfma_f32_16x16x32_bf16 v[46:49], v[204:207], v[98:101], v[46:49]
	ds_read_b128 v[204:207], v183 offset:61056
	s_waitcnt lgkmcnt(1)
	v_mfma_f32_16x16x32_bf16 v[38:41], v[200:203], v[124:127], v[38:41]
	v_mfma_f32_16x16x32_bf16 v[46:49], v[200:203], v[128:131], v[46:49]
	ds_read_b128 v[200:203], v183 offset:61120
	s_waitcnt lgkmcnt(1)
	v_mfma_f32_16x16x32_bf16 v[26:29], v[204:207], v[94:97], v[26:29]
	v_mfma_f32_16x16x32_bf16 v[30:33], v[204:207], v[98:101], v[30:33]
	ds_read_b128 v[204:207], v183 offset:65408
	s_waitcnt lgkmcnt(1)
	v_mfma_f32_16x16x32_bf16 v[26:29], v[200:203], v[124:127], v[26:29]
	v_mfma_f32_16x16x32_bf16 v[30:33], v[200:203], v[128:131], v[30:33]
	s_waitcnt lgkmcnt(0)
	v_mfma_f32_16x16x32_bf16 v[18:21], v[204:207], v[94:97], v[18:21]
	v_mfma_f32_16x16x32_bf16 v[22:25], v[204:207], v[98:101], v[22:25]
	ds_read_b128 v[58:61], v183 offset:65472
	s_waitcnt lgkmcnt(0)
	s_barrier
	v_mfma_f32_16x16x32_bf16 v[18:21], v[58:61], v[124:127], v[18:21]
	v_mfma_f32_16x16x32_bf16 v[22:25], v[58:61], v[128:131], v[22:25]
	v_add_f32_e64 v58, v172, 0
	v_add_f32_e64 v59, v173, 0
	v_add_f32_e32 v60, v122, v118
	v_pk_add_f32 v[58:59], v[174:175], v[58:59]
	v_add_f32_e32 v60, v60, v119
	v_pk_add_f32 v[58:59], v[170:171], v[58:59]
	s_nop 0
	v_pk_add_f32 v[58:59], v[166:167], v[58:59]
	s_nop 0
	v_pk_add_f32 v[58:59], v[58:59], v[168:169]
	s_nop 0
	v_pk_add_f32 v[58:59], v[164:165], v[58:59]
	s_nop 0
	v_pk_add_f32 v[58:59], v[160:161], v[58:59]
	s_nop 0
	v_pk_add_f32 v[58:59], v[162:163], v[58:59]
	s_nop 0
	v_add_f32_e32 v58, v60, v58
	v_pk_add_f32 v[60:61], v[116:117], 0 op_sel_hi:[1,0]
	v_add_f32_e32 v62, v58, v59
	v_pk_add_f32 v[60:61], v[114:115], v[60:61]
	v_pk_add_f32 v[58:59], v[158:159], 0 op_sel_hi:[1,0]
	v_pk_add_f32 v[60:61], v[112:113], v[60:61]
	v_pk_add_f32 v[58:59], v[156:157], v[58:59]
	v_pk_add_f32 v[60:61], v[110:111], v[60:61]
	v_pk_add_f32 v[58:59], v[154:155], v[58:59]
	v_pk_add_f32 v[60:61], v[60:61], v[108:109]
	v_pk_add_f32 v[58:59], v[144:145], v[58:59]
	v_pk_add_f32 v[60:61], v[106:107], v[60:61]
	v_pk_add_f32 v[58:59], v[58:59], v[142:143]
	v_pk_add_f32 v[60:61], v[104:105], v[60:61]
	v_pk_add_f32 v[58:59], v[140:141], v[58:59]
	v_pk_add_f32 v[60:61], v[102:103], v[60:61]
	v_pk_add_f32 v[58:59], v[138:139], v[58:59]
	v_add_f32_e32 v60, v123, v60
	v_pk_add_f32 v[58:59], v[136:137], v[58:59]
	v_add_f32_e32 v60, v60, v61
	v_add_f32_e32 v58, v60, v58
	v_add_f32_e32 v58, v58, v59
	v_add_f32_e32 v59, v186, v187
	v_mul_f32_e32 v60, 0x3fb8aa3b, v59
	v_fma_f32 v61, v59, s10, -v60
	v_rndne_f32_e32 v63, v60
	v_fmac_f32_e32 v61, 0x32a5705f, v59
	v_sub_f32_e32 v60, v60, v63
	v_add_f32_e32 v60, v60, v61
	v_exp_f32_e32 v60, v60
	v_cvt_i32_f32_e32 v61, v63
	v_cmp_ngt_f32_e32 vcc, s11, v59
	v_ldexp_f32 v60, v60, v61
	s_nop 0
	v_cndmask_b32_e32 v60, 0, v60, vcc
	v_cmp_nlt_f32_e32 vcc, s6, v59
	s_nop 1
	v_cndmask_b32_e32 v59, v220, v60, vcc
	v_add_f32_e32 v60, v184, v185
	v_mul_f32_e32 v61, 0x3fb8aa3b, v60
	v_fma_f32 v63, v60, s10, -v61
	v_rndne_f32_e32 v64, v61
	v_fmac_f32_e32 v63, 0x32a5705f, v60
	v_sub_f32_e32 v61, v61, v64
	v_add_f32_e32 v61, v61, v63
	v_exp_f32_e32 v61, v61
	v_cvt_i32_f32_e32 v63, v64
	v_cmp_ngt_f32_e32 vcc, s11, v60
	v_ldexp_f32 v61, v61, v63
	s_nop 0
	v_cndmask_b32_e32 v61, 0, v61, vcc
	v_cmp_nlt_f32_e32 vcc, s6, v60
	s_movk_i32 s6, 0x200
	s_nop 0
	v_cndmask_b32_e32 v60, v220, v61, vcc
	v_sub_f32_e32 v59, v59, v60
	ds_bpermute_b32 v60, v176, v58
	v_add_f32_e32 v59, v236, v59
	v_cndmask_b32_e64 v59, -v59, 1.0, s[40:41]
	s_waitcnt lgkmcnt(0)
	v_add_f32_e32 v58, v58, v60
	ds_bpermute_b32 v60, v1, v58
	s_waitcnt lgkmcnt(0)
	v_add_f32_e32 v58, v58, v60
	ds_bpermute_b32 v60, v176, v62
	s_waitcnt lgkmcnt(0)
	v_add_f32_e32 v60, v62, v60
	ds_bpermute_b32 v61, v1, v60
	s_waitcnt lgkmcnt(0)
	v_add_f32_e32 v60, v60, v61
	v_div_scale_f32 v61, s[10:11], v58, v58, v59
	v_rcp_f32_e32 v62, v61
	s_nop 0
	v_fma_f32 v63, -v61, v62, 1.0
	v_fmac_f32_e32 v62, v63, v62
	v_div_scale_f32 v63, vcc, v59, v58, v59
	v_mul_f32_e32 v64, v63, v62
	v_fma_f32 v65, -v61, v64, v63
	v_fmac_f32_e32 v64, v65, v62
	v_fma_f32 v61, -v61, v64, v63
	v_div_fmas_f32 v61, v61, v62, v64
	v_div_fixup_f32 v62, v61, v58, v59
	v_div_scale_f32 v58, s[10:11], v60, v60, v59
	v_rcp_f32_e32 v61, v58
	s_nop 0
	v_fma_f32 v63, -v58, v61, 1.0
	v_fmac_f32_e32 v61, v63, v61
	v_div_scale_f32 v63, vcc, v59, v60, v59
	v_mul_f32_e32 v64, v63, v61
	v_fma_f32 v65, -v58, v64, v63
	v_fmac_f32_e32 v64, v65, v61
	v_fma_f32 v58, -v58, v64, v63
	v_div_fmas_f32 v58, v58, v61, v64
	v_div_fixup_f32 v64, v58, v60, v59
	v_lshlrev_b32_e32 v58, 13, v182
	v_lshlrev_b32_e32 v59, 4, v181
	v_pk_mul_f32 v[66:67], v[90:91], v[64:65] op_sel_hi:[1,0]
	v_pk_mul_f32 v[68:69], v[92:93], v[64:65] op_sel_hi:[1,0]
	v_pk_mul_f32 v[70:71], v[78:79], v[62:63] op_sel_hi:[1,0]
	v_pk_mul_f32 v[72:73], v[80:81], v[62:63] op_sel_hi:[1,0]
	v_pk_mul_f32 v[74:75], v[10:11], v[64:65] op_sel_hi:[1,0]
	v_pk_mul_f32 v[76:77], v[12:13], v[64:65] op_sel_hi:[1,0]
	v_pk_mul_f32 v[78:79], v[2:3], v[62:63] op_sel_hi:[1,0]
	v_pk_mul_f32 v[80:81], v[4:5], v[62:63] op_sel_hi:[1,0]
	v_add3_u32 v84, 0, v58, v59
	v_cndmask_b32_e64 v61, v73, v69, s[40:41]
	v_cndmask_b32_e64 v60, v72, v68, s[40:41]
	v_cndmask_b32_e64 v59, v71, v67, s[40:41]
	v_cndmask_b32_e64 v58, v70, v66, s[40:41]
	v_cndmask_b32_e64 v5, v81, v77, s[40:41]
	v_cndmask_b32_e64 v4, v80, v76, s[40:41]
	v_cndmask_b32_e64 v3, v79, v75, s[40:41]
	v_cndmask_b32_e64 v2, v78, v74, s[40:41]
	v_pk_mul_f32 v[54:55], v[54:55], v[64:65] op_sel_hi:[1,0]
	v_pk_mul_f32 v[56:57], v[56:57], v[64:65] op_sel_hi:[1,0]
	v_pk_mul_f32 v[42:43], v[42:43], v[62:63] op_sel_hi:[1,0]
	v_pk_mul_f32 v[44:45], v[44:45], v[62:63] op_sel_hi:[1,0]
	ds_write_b128 v84, v[58:61]
	v_pk_mul_f32 v[50:51], v[50:51], v[64:65] op_sel_hi:[1,0]
	v_pk_mul_f32 v[52:53], v[52:53], v[64:65] op_sel_hi:[1,0]
	v_pk_mul_f32 v[58:59], v[14:15], v[62:63] op_sel_hi:[1,0]
	v_pk_mul_f32 v[60:61], v[16:17], v[62:63] op_sel_hi:[1,0]
	ds_write_b128 v84, v[2:5] offset:3072
	v_cndmask_b32_e64 v5, v45, v57, s[40:41]
	v_cndmask_b32_e64 v4, v44, v56, s[40:41]
	v_cndmask_b32_e64 v3, v43, v55, s[40:41]
	v_cndmask_b32_e64 v2, v42, v54, s[40:41]
	v_pk_mul_f32 v[46:47], v[46:47], v[64:65] op_sel_hi:[1,0]
	v_pk_mul_f32 v[48:49], v[48:49], v[64:65] op_sel_hi:[1,0]
	v_pk_mul_f32 v[38:39], v[38:39], v[62:63] op_sel_hi:[1,0]
	v_pk_mul_f32 v[82:83], v[40:41], v[62:63] op_sel_hi:[1,0]
	v_cndmask_b32_e64 v17, v61, v53, s[40:41]
	v_cndmask_b32_e64 v16, v60, v52, s[40:41]
	v_cndmask_b32_e64 v15, v59, v51, s[40:41]
	v_cndmask_b32_e64 v14, v58, v50, s[40:41]
	ds_write_b128 v84, v[2:5] offset:4096
	v_cndmask_b32_e64 v5, v83, v49, s[40:41]
	v_cndmask_b32_e64 v4, v82, v48, s[40:41]
	v_cndmask_b32_e64 v3, v39, v47, s[40:41]
	v_cndmask_b32_e64 v2, v38, v46, s[40:41]
	v_pk_mul_f32 v[30:31], v[30:31], v[64:65] op_sel_hi:[1,0]
	v_pk_mul_f32 v[32:33], v[32:33], v[64:65] op_sel_hi:[1,0]
	v_pk_mul_f32 v[26:27], v[26:27], v[62:63] op_sel_hi:[1,0]
	v_pk_mul_f32 v[28:29], v[28:29], v[62:63] op_sel_hi:[1,0]
	ds_write_b128 v84, v[14:17] offset:1024
	v_pk_mul_f32 v[14:15], v[34:35], v[64:65] op_sel_hi:[1,0]
	v_pk_mul_f32 v[16:17], v[36:37], v[64:65] op_sel_hi:[1,0]
	v_pk_mul_f32 v[34:35], v[6:7], v[62:63] op_sel_hi:[1,0]
	v_pk_mul_f32 v[36:37], v[8:9], v[62:63] op_sel_hi:[1,0]
	ds_write_b128 v84, v[2:5] offset:5120
	v_cndmask_b32_e64 v5, v29, v33, s[40:41]
	v_cndmask_b32_e64 v4, v28, v32, s[40:41]
	v_cndmask_b32_e64 v3, v27, v31, s[40:41]
	v_cndmask_b32_e64 v2, v26, v30, s[40:41]
	v_pk_mul_f32 v[22:23], v[22:23], v[64:65] op_sel_hi:[1,0]
	v_pk_mul_f32 v[24:25], v[24:25], v[64:65] op_sel_hi:[1,0]
	v_pk_mul_f32 v[64:65], v[18:19], v[62:63] op_sel_hi:[1,0]
	v_pk_mul_f32 v[62:63], v[20:21], v[62:63] op_sel_hi:[1,0]
	ds_write_b128 v84, v[2:5] offset:6144
	v_cndmask_b32_e64 v5, v63, v25, s[40:41]
	v_cndmask_b32_e64 v4, v62, v24, s[40:41]
	v_cndmask_b32_e64 v3, v65, v23, s[40:41]
	v_cndmask_b32_e64 v2, v64, v22, s[40:41]
	ds_write_b128 v84, v[2:5] offset:7168
	v_lshlrev_b32_e32 v2, 9, v182
	v_cndmask_b32_e64 v9, v37, v17, s[40:41]
	v_cndmask_b32_e64 v8, v36, v16, s[40:41]
	v_cndmask_b32_e64 v7, v35, v15, s[40:41]
	v_cndmask_b32_e64 v6, v34, v14, s[40:41]
	v_bitop3_b32 v2, v2, s6, v181 bitop3:0x36
	ds_write_b128 v84, v[6:9] offset:2048
	v_lshl_add_u32 v84, v2, 4, 0
	s_waitcnt lgkmcnt(0)
	s_barrier
	s_add_u32 s100, s100, s14
	s_addc_u32 s101, s101, s15
	v_lshlrev_b32_e32 v132, 4, v178
	global_load_dwordx4 v[100:103], v132, s[100:101]
	global_load_dwordx4 v[104:107], v132, s[100:101] offset:64
	global_load_dwordx4 v[108:111], v132, s[100:101] offset:128
	global_load_dwordx4 v[112:115], v132, s[100:101] offset:192
	global_load_dwordx4 v[116:119], v132, s[100:101] offset:256
	global_load_dwordx4 v[120:123], v132, s[100:101] offset:320
	global_load_dwordx4 v[124:127], v132, s[100:101] offset:384
	global_load_dwordx4 v[128:131], v132, s[100:101] offset:448
	ds_read_b128 v[2:5], v84
	ds_read_b128 v[6:9], v84 offset:1024
	v_cndmask_b32_e64 v67, v67, v71, s[40:41]
	v_cndmask_b32_e64 v66, v66, v70, s[40:41]
	v_cndmask_b32_e64 v69, v69, v73, s[40:41]
	v_cndmask_b32_e64 v68, v68, v72, s[40:41]
	v_cndmask_b32_e64 v73, v75, v79, s[40:41]
	v_cndmask_b32_e64 v72, v74, v78, s[40:41]
	v_cndmask_b32_e64 v75, v77, v81, s[40:41]
	v_cndmask_b32_e64 v74, v76, v80, s[40:41]
	v_cndmask_b32_e64 v77, v47, v39, s[40:41]
	v_cndmask_b32_e64 v76, v46, v38, s[40:41]
	s_waitcnt lgkmcnt(1)
	v_pk_add_f32 v[38:39], v[66:67], v[2:3]
	v_cndmask_b32_e64 v71, v17, v37, s[40:41]
	v_mul_f32_e32 v66, v39, v39
	v_cndmask_b32_e64 v70, v16, v36, s[40:41]
	v_pk_add_f32 v[36:37], v[68:69], v[4:5]
	v_fmac_f32_e32 v66, v38, v38
	v_cndmask_b32_e64 v59, v51, v59, s[40:41]
	v_cndmask_b32_e64 v58, v50, v58, s[40:41]
	ds_read_b128 v[10:13], v84 offset:2048
	v_fmac_f32_e32 v66, v36, v36
	v_cndmask_b32_e64 v53, v53, v61, s[40:41]
	v_cndmask_b32_e64 v52, v52, v60, s[40:41]
	v_cndmask_b32_e64 v61, v15, v35, s[40:41]
	v_cndmask_b32_e64 v60, v14, v34, s[40:41]
	v_fmac_f32_e32 v66, v37, v37
	s_waitcnt lgkmcnt(1)
	v_pk_add_f32 v[34:35], v[58:59], v[6:7]
	v_cndmask_b32_e64 v79, v49, v83, s[40:41]
	v_fmac_f32_e32 v66, v34, v34
	v_cndmask_b32_e64 v78, v48, v82, s[40:41]
	v_cndmask_b32_e64 v83, v33, v29, s[40:41]
	v_cndmask_b32_e64 v82, v32, v28, s[40:41]
	v_pk_add_f32 v[32:33], v[52:53], v[8:9]
	v_fmac_f32_e32 v66, v35, v35
	ds_read_b128 v[14:17], v84 offset:3072
	v_fmac_f32_e32 v66, v32, v32
	v_cndmask_b32_e64 v81, v31, v27, s[40:41]
	v_cndmask_b32_e64 v80, v30, v26, s[40:41]
	v_fmac_f32_e32 v66, v33, v33
	s_waitcnt lgkmcnt(1)
	v_pk_add_f32 v[30:31], v[60:61], v[10:11]
	v_pk_add_f32 v[28:29], v[70:71], v[12:13]
	v_fmac_f32_e32 v66, v30, v30
	v_fmac_f32_e32 v66, v31, v31
	ds_read_b128 v[18:21], v84 offset:4096
	v_fmac_f32_e32 v66, v28, v28
	v_fmac_f32_e32 v66, v29, v29
	s_waitcnt lgkmcnt(1)
	v_pk_add_f32 v[26:27], v[72:73], v[14:15]
	v_cndmask_b32_e64 v63, v25, v63, s[40:41]
	v_fmac_f32_e32 v66, v26, v26
	v_cndmask_b32_e64 v62, v24, v62, s[40:41]
	v_pk_add_f32 v[24:25], v[74:75], v[16:17]
	v_fmac_f32_e32 v66, v27, v27
	v_cndmask_b32_e64 v55, v55, v43, s[40:41]
	v_cndmask_b32_e64 v54, v54, v42, s[40:41]
	ds_read_b128 v[40:43], v84 offset:5120
	v_fmac_f32_e32 v66, v24, v24
	v_cndmask_b32_e64 v65, v23, v65, s[40:41]
	v_cndmask_b32_e64 v64, v22, v64, s[40:41]
	v_fmac_f32_e32 v66, v25, v25
	s_waitcnt lgkmcnt(1)
	v_pk_add_f32 v[22:23], v[54:55], v[18:19]
	v_cndmask_b32_e64 v57, v57, v45, s[40:41]
	v_cndmask_b32_e64 v56, v56, v44, s[40:41]
	v_fmac_f32_e32 v66, v22, v22
	ds_read_b128 v[44:47], v84 offset:6144
	ds_read_b128 v[48:51], v84 offset:7168
	v_pk_add_f32 v[20:21], v[56:57], v[20:21]
	v_fmac_f32_e32 v66, v23, v23
	v_fmac_f32_e32 v66, v20, v20
	v_fmac_f32_e32 v66, v21, v21
	s_waitcnt lgkmcnt(2)
	v_pk_add_f32 v[18:19], v[76:77], v[40:41]
	v_pk_add_f32 v[16:17], v[78:79], v[42:43]
	v_fmac_f32_e32 v66, v18, v18
	v_fmac_f32_e32 v66, v19, v19
	v_fmac_f32_e32 v66, v16, v16
	s_waitcnt lgkmcnt(1)
	v_pk_add_f32 v[14:15], v[80:81], v[44:45]
	v_fmac_f32_e32 v66, v17, v17
	v_pk_mul_f32 v[4:5], v[14:15], v[14:15]
	v_pk_add_f32 v[12:13], v[82:83], v[46:47]
	v_add_f32_e32 v4, v4, v66
	v_pk_mul_f32 v[2:3], v[12:13], v[12:13]
	v_add_f32_e32 v4, v5, v4
	v_add_f32_e32 v2, v2, v4
	s_waitcnt lgkmcnt(0)
	v_pk_add_f32 v[8:9], v[64:65], v[48:49]
	v_add_f32_e32 v10, v3, v2
	v_pk_mul_f32 v[4:5], v[8:9], v[8:9]
	v_pk_add_f32 v[6:7], v[62:63], v[50:51]
	v_add_f32_e32 v4, v4, v10
	v_pk_mul_f32 v[2:3], v[6:7], v[6:7]
	v_add_f32_e32 v4, v5, v4
	v_add_f32_e32 v2, v2, v4
	v_add_f32_e32 v2, v3, v2
	ds_bpermute_b32 v3, v176, v2
	s_load_dwordx2 s[10:11], s[44:45], 0x80
	v_lshlrev_b32_e32 v4, 3, v178
	v_mov_b32_e32 v5, v0
	s_mov_b32 s6, 0x18a10000
	s_waitcnt lgkmcnt(0)
	v_add_f32_e32 v2, v2, v3
	ds_bpermute_b32 v1, v1, v2
	s_add_u32 s10, s10, s14
	s_addc_u32 s11, s11, s15
	s_mov_b64 s[14:15], 0x18a10000
	v_lshlrev_b32_e32 v44, 4, v178
	s_waitcnt lgkmcnt(0)
	v_add_f32_e32 v1, v2, v1
	v_fmamk_f32 v1, v1, 0x3c000000, v234
	v_cmp_gt_f32_e32 vcc, s90, v1
	v_mul_f32_e32 v2, 0x4b800000, v1
	s_nop 0
	v_cndmask_b32_e32 v1, v1, v2, vcc
	v_rsq_f32_e32 v1, v1
	s_nop 0
	v_mul_f32_e32 v2, 0x45800000, v1
	v_cndmask_b32_e32 v1, v1, v2, vcc
	v_lshlrev_b32_e32 v2, 4, v179
	v_or3_b32 v2, v2, v177, v180
	v_ashrrev_i32_e32 v3, 31, v2
	v_lshlrev_b64 v[2:3], 11, v[2:3]
	v_lshl_add_u64 v[2:3], s[42:43], 0, v[2:3]
	v_lshl_add_u64 v[2:3], v[2:3], 0, s[30:31]
	v_lshl_add_u64 v[2:3], v[2:3], 0, v[4:5]
	v_add_co_u32_e32 v40, vcc, s6, v2
	v_lshl_add_u64 v[10:11], v[2:3], 0, s[14:15]
	s_nop 0
	v_addc_co_u32_e32 v41, vcc, 0, v3, vcc
	v_mul_f32_e32 v1, v227, v1
	v_mul_f32_e32 v38, v38, v1
	v_mul_f32_e32 v36, v36, v1
	v_mul_f32_e32 v34, v34, v1
	v_mul_f32_e32 v32, v32, v1
	v_mul_f32_e32 v30, v30, v1
	v_mul_f32_e32 v28, v28, v1
	v_mul_f32_e32 v26, v26, v1
	v_mul_f32_e32 v24, v24, v1
	v_mul_f32_e32 v22, v22, v1
	v_mul_f32_e32 v20, v20, v1
	v_mul_f32_e32 v18, v18, v1
	v_mul_f32_e32 v16, v16, v1
	v_mul_f32_e32 v14, v14, v1
	v_mul_f32_e32 v12, v12, v1
	s_waitcnt vmcnt(0)
	v_readfirstlane_b32 s101, v224
	v_mov_b32_e32 v42, v146
	v_mov_b32_e32 v43, v147
	v_mov_b32_e32 v2, v100
	v_mov_b32_e32 v3, v101
	v_mov_b32_e32 v4, v102
	v_mov_b32_e32 v5, v103
	v_mul_f32_e32 v2, v2, v38
	v_lshlrev_b32_e32 v38, 16, v42
	v_mul_f32_e32 v2, v2, v38
	v_mul_f32_e32 v38, v39, v1
	v_mul_f32_e32 v4, v4, v36
	v_lshlrev_b32_e32 v36, 16, v43
	v_mul_f32_e32 v3, v3, v38
	v_and_b32_e32 v38, 0xffff0000, v42
	v_mul_f32_e32 v4, v4, v36
	v_mul_f32_e32 v36, v37, v1
	v_mul_f32_e32 v3, v3, v38
	v_mul_f32_e32 v5, v5, v36
	v_and_b32_e32 v36, 0xffff0000, v43
	v_mul_f32_e32 v5, v5, v36
	s_nop 1
	v_cvt_pk_bf16_f32 v2, v2, v3
	s_nop 1
	v_cvt_pk_bf16_f32 v3, v4, v5
	global_store_dwordx2 v[40:41], v[2:3], off
	v_mov_b32_e32 v36, v148
	v_mov_b32_e32 v37, v149
	s_nop 0
	v_mov_b32_e32 v2, v104
	v_mov_b32_e32 v3, v105
	v_mov_b32_e32 v4, v106
	v_mov_b32_e32 v5, v107
	v_mul_f32_e32 v2, v2, v34
	v_lshlrev_b32_e32 v34, 16, v36
	v_mul_f32_e32 v2, v2, v34
	v_mul_f32_e32 v34, v35, v1
	v_mul_f32_e32 v4, v4, v32
	v_lshlrev_b32_e32 v32, 16, v37
	v_mul_f32_e32 v3, v3, v34
	v_and_b32_e32 v34, 0xffff0000, v36
	v_mul_f32_e32 v4, v4, v32
	v_mul_f32_e32 v32, v33, v1
	v_mul_f32_e32 v3, v3, v34
	v_mul_f32_e32 v5, v5, v32
	v_and_b32_e32 v32, 0xffff0000, v37
	v_mul_f32_e32 v5, v5, v32
	s_nop 1
	v_cvt_pk_bf16_f32 v2, v2, v3
	s_nop 1
	v_cvt_pk_bf16_f32 v3, v4, v5
	global_store_dwordx2 v[10:11], v[2:3], off offset:32
	v_mov_b32_e32 v32, v150
	v_mov_b32_e32 v33, v151
	s_nop 0
	v_mov_b32_e32 v2, v108
	v_mov_b32_e32 v3, v109
	v_mov_b32_e32 v4, v110
	v_mov_b32_e32 v5, v111
	v_mul_f32_e32 v2, v2, v30
	v_lshlrev_b32_e32 v30, 16, v32
	v_mul_f32_e32 v2, v2, v30
	v_mul_f32_e32 v30, v31, v1
	v_mul_f32_e32 v4, v4, v28
	v_lshlrev_b32_e32 v28, 16, v33
	v_mul_f32_e32 v3, v3, v30
	v_and_b32_e32 v30, 0xffff0000, v32
	v_mul_f32_e32 v4, v4, v28
	v_mul_f32_e32 v28, v29, v1
	v_mul_f32_e32 v3, v3, v30
	v_mul_f32_e32 v5, v5, v28
	v_and_b32_e32 v28, 0xffff0000, v33
	v_mul_f32_e32 v5, v5, v28
	s_nop 1
	v_cvt_pk_bf16_f32 v2, v2, v3
	s_nop 1
	v_cvt_pk_bf16_f32 v3, v4, v5
	global_store_dwordx2 v[10:11], v[2:3], off offset:64
	v_mov_b32_e32 v28, v152
	v_mov_b32_e32 v29, v153
	s_nop 0
	v_mov_b32_e32 v2, v112
	v_mov_b32_e32 v3, v113
	v_mov_b32_e32 v4, v114
	v_mov_b32_e32 v5, v115
	v_mul_f32_e32 v2, v2, v26
	v_lshlrev_b32_e32 v26, 16, v28
	v_mul_f32_e32 v2, v2, v26
	v_mul_f32_e32 v26, v27, v1
	v_mul_f32_e32 v4, v4, v24
	v_lshlrev_b32_e32 v24, 16, v29
	v_mul_f32_e32 v3, v3, v26
	v_and_b32_e32 v26, 0xffff0000, v28
	v_mul_f32_e32 v4, v4, v24
	v_mul_f32_e32 v24, v25, v1
	v_mul_f32_e32 v3, v3, v26
	v_mul_f32_e32 v5, v5, v24
	v_and_b32_e32 v24, 0xffff0000, v29
	v_mul_f32_e32 v5, v5, v24
	s_nop 1
	v_cvt_pk_bf16_f32 v2, v2, v3
	s_nop 1
	v_cvt_pk_bf16_f32 v3, v4, v5
	global_store_dwordx2 v[10:11], v[2:3], off offset:96
	v_mov_b32_e32 v24, v188
	v_mov_b32_e32 v25, v189
	s_nop 0
	v_mov_b32_e32 v2, v116
	v_mov_b32_e32 v3, v117
	v_mov_b32_e32 v4, v118
	v_mov_b32_e32 v5, v119
	v_mul_f32_e32 v2, v2, v22
	v_lshlrev_b32_e32 v22, 16, v24
	v_mul_f32_e32 v2, v2, v22
	v_mul_f32_e32 v22, v23, v1
	v_mul_f32_e32 v4, v4, v20
	v_lshlrev_b32_e32 v20, 16, v25
	v_mul_f32_e32 v3, v3, v22
	v_and_b32_e32 v22, 0xffff0000, v24
	v_mul_f32_e32 v4, v4, v20
	v_mul_f32_e32 v20, v21, v1
	v_mul_f32_e32 v3, v3, v22
	v_mul_f32_e32 v5, v5, v20
	v_and_b32_e32 v20, 0xffff0000, v25
	v_mul_f32_e32 v5, v5, v20
	s_nop 1
	v_cvt_pk_bf16_f32 v2, v2, v3
	s_nop 1
	v_cvt_pk_bf16_f32 v3, v4, v5
	global_store_dwordx2 v[10:11], v[2:3], off offset:128
	v_mov_b32_e32 v20, v190
	v_mov_b32_e32 v21, v191
	s_nop 0
	v_mov_b32_e32 v2, v120
	v_mov_b32_e32 v3, v121
	v_mov_b32_e32 v4, v122
	v_mov_b32_e32 v5, v123
	v_mul_f32_e32 v2, v2, v18
	v_lshlrev_b32_e32 v18, 16, v20
	v_mul_f32_e32 v2, v2, v18
	v_mul_f32_e32 v18, v19, v1
	v_mul_f32_e32 v4, v4, v16
	v_lshlrev_b32_e32 v16, 16, v21
	v_mul_f32_e32 v3, v3, v18
	v_and_b32_e32 v18, 0xffff0000, v20
	v_mul_f32_e32 v4, v4, v16
	v_mul_f32_e32 v16, v17, v1
	v_mul_f32_e32 v3, v3, v18
	v_mul_f32_e32 v5, v5, v16
	v_and_b32_e32 v16, 0xffff0000, v21
	v_mul_f32_e32 v5, v5, v16
	s_nop 1
	v_cvt_pk_bf16_f32 v2, v2, v3
	s_nop 1
	v_cvt_pk_bf16_f32 v3, v4, v5
	global_store_dwordx2 v[10:11], v[2:3], off offset:160
	v_mov_b32_e32 v16, v192
	v_mov_b32_e32 v17, v193
	s_nop 0
	v_mov_b32_e32 v2, v124
	v_mov_b32_e32 v3, v125
	v_mov_b32_e32 v4, v126
	v_mov_b32_e32 v5, v127
	v_mul_f32_e32 v2, v2, v14
	v_lshlrev_b32_e32 v14, 16, v16
	v_mul_f32_e32 v2, v2, v14
	v_mul_f32_e32 v14, v15, v1
	v_mul_f32_e32 v4, v4, v12
	v_lshlrev_b32_e32 v12, 16, v17
	v_mul_f32_e32 v3, v3, v14
	v_and_b32_e32 v14, 0xffff0000, v16
	v_mul_f32_e32 v4, v4, v12
	v_mul_f32_e32 v12, v13, v1
	v_mul_f32_e32 v3, v3, v14
	v_mul_f32_e32 v5, v5, v12
	v_and_b32_e32 v12, 0xffff0000, v17
	v_mul_f32_e32 v5, v5, v12
	s_nop 1
	v_cvt_pk_bf16_f32 v2, v2, v3
	s_nop 1
	v_cvt_pk_bf16_f32 v3, v4, v5
	global_store_dwordx2 v[10:11], v[2:3], off offset:192
	v_mov_b32_e32 v2, v194
	v_mov_b32_e32 v3, v195
	s_nop 0
	v_mov_b32_e32 v12, v128
	v_mov_b32_e32 v13, v129
	v_mov_b32_e32 v14, v130
	v_mov_b32_e32 v15, v131
	v_mul_f32_e32 v4, v8, v1
	v_lshlrev_b32_e32 v5, 16, v2
	v_mul_f32_e32 v4, v4, v12
	v_mul_f32_e32 v4, v4, v5
	v_mul_f32_e32 v5, v9, v1
	v_mul_f32_e32 v5, v5, v13
	v_and_b32_e32 v2, 0xffff0000, v2
	v_mul_f32_e32 v2, v5, v2
	v_mul_f32_e32 v5, v6, v1
	v_mul_f32_e32 v1, v7, v1
	v_mul_f32_e32 v5, v5, v14
	v_lshlrev_b32_e32 v6, 16, v3
	v_mul_f32_e32 v1, v1, v15
	v_and_b32_e32 v3, 0xffff0000, v3
	v_mul_f32_e32 v5, v5, v6
	v_mul_f32_e32 v1, v1, v3
	s_nop 1
	v_cvt_pk_bf16_f32 v2, v4, v2
	s_nop 1
	v_cvt_pk_bf16_f32 v3, v5, v1
	global_store_dwordx2 v[10:11], v[2:3], off offset:224
	s_barrier
